# v60 + attention: far-tile bias constant by s_cselect (no taken branches on the common path), near-diagonal blocks out of line
# baseline (speedup 1.0000x reference)
; template <int D0, int S> __device__ __forceinline__ VG vload(ldsc_t vb) { VG g; g.l0 = vtr(vb + v_rd_off(D0, 2 * S, 0)); g.h0 = vtr(vb + v_rd_off(D0, 2 * S, 1)); g.l1 = vtr(vb + v_rd_off(D0, 2 * S + 1, 0)); g.h1 = vtr(vb + v_rd_off(D0, 2 * S + 1, 1)); return g; }
; #define DMA_K1(g_, b, i_) __builtin_amdgcn_global_load_lds((const unsigned*)((g_) + (((i_) & 1) * 32 * LD * 2 + ((i_) >> 1) * 256) + koff0), (__attribute__((address_space(3))) unsigned*)(ldsb + (b) * STAGE + (wid + 8 * (i_)) * 1024), 16, 0, 0)
; __device__ __forceinline__ void softmax_sub(f32x16& p, float& m_reg, float& l_reg, bf16x8& pa0, bf16x8& pa1, f32x16 (&o)[8], float* al_l, int r32, int hi, int dj, const float* tab, float cL, float cR) {
;     ...
;   if (dj <= -159) cb = cL;
;   else if (dj >= 159) cb = cR;
;   else { cb = 0.f; const int ib = dj - r32 + 4 * hi + 128;
; #pragma unroll
;     for (int r = 0; r < 16; ++r) { const int i0 = ib + (r & 3) + 8 * (r >> 2); p[r] += tab[min(max(i0, 0), 256)]; } }
; __device__ __forceinline__ void attn_unit(const bf16* __restrict__ qkvb, int seq, int q0, int h, ldsp_t ldsb, float* wsc, const float* tab, float lam) {
;     ...
;     const int bo = (j & 1) * STAGE; const int bn = (j + 1) & 1; const bool more = j + 1 < NT;
;     const char* gn = kvb + (long)(j + 1) * tstep;
;     asm volatile("s_waitcnt vmcnt(0)" ::: "memory");
;     asm volatile("" ::: "memory"); __builtin_amdgcn_s_barrier(); asm volatile("" ::: "memory");
;     {
;       f32x16 p0, p1; bf16x8 pa0, pa1;
;       qk_sub(p0, kp[0] + bo, kp[1] + bo, kp[2] + bo, kp[3] + bo, kd, qr, [&](int i) { if (more) DMA_K1(gn, bn, i); });
;       qk_sub(p1, kp[0] + bo + 8192, kp[1] + bo + 8192, kp[2] + bo + 8192, kp[3] + bo + 8192, kd, qr, [](int) {});
;       { VG g0 = vload<0, 0>(vp + bo), g1 = vload<1, 0>(vp + bo);
;         softmax_sub(p0, m_reg, l_reg, pa0, pa1, o, al_l, r32, hi, 64 * j - q0w, tab, cL, cR);
.LBB0_548:
	s_waitcnt vmcnt(0)
	s_add_i32 s4, s27, 0xffff0000
	s_barrier
	s_and_b32 s29, s4, 0x10000
	v_add_u32_e32 v1, s29, v252
	v_add_u32_e32 v198, s29, v253
	v_add_u32_e32 v199, s29, v241
	v_add_u32_e32 v202, s29, v244
	ds_read_b128 v[130:133], v1
	ds_read_b128 v[134:137], v198
	ds_read_b128 v[138:141], v199
	ds_read_b128 v[142:145], v202
	s_setprio 1
	s_waitcnt lgkmcnt(0)
	v_mfma_f32_32x32x16_bf16 v[146:161], v[130:133], v[190:193], 0
	v_add_u32_e32 v206, v1, v251
	ds_read_b128 v[130:133], v206
	s_and_b32 s24, s27, 0x10000
	s_add_i32 s28, s23, s24
	v_add_u32_e32 v210, v198, v251
	v_mfma_f32_32x32x16_bf16 v[146:161], v[134:137], v[186:189], v[146:161]
	ds_read_b128 v[134:137], v210
	s_add_u32 s4, s8, 0xc0000
	s_addc_u32 s5, s9, 0
	s_mov_b32 m0, s28
	s_nop 0
	global_load_lds_dwordx4 v226, s[4:5]
	v_mfma_f32_32x32x16_bf16 v[146:161], v[138:141], v[182:185], v[146:161]
	v_add_u32_e32 v212, v199, v251
	ds_read_b128 v[138:141], v212
	v_add_u32_e32 v213, v202, v251
	v_mfma_f32_32x32x16_bf16 v[146:161], v[142:145], v[178:181], v[146:161]
	ds_read_b128 v[142:145], v213
	s_add_u32 s4, s8, 0x120000
	s_addc_u32 s5, s9, 0
	s_add_i32 m0, s28, 0x2000
	s_nop 0
	global_load_lds_dwordx4 v226, s[4:5]
	s_waitcnt lgkmcnt(0)
	v_mfma_f32_32x32x16_bf16 v[146:161], v[130:133], v[174:177], v[146:161]
	s_add_u32 s4, s8, 0xc0100
	s_addc_u32 s5, s9, 0
	s_add_i32 m0, s28, 0x4000
	s_nop 0
	global_load_lds_dwordx4 v226, s[4:5]
	v_mfma_f32_32x32x16_bf16 v[146:161], v[134:137], v[170:173], v[146:161]
	v_mfma_f32_32x32x16_bf16 v[146:161], v[138:141], v[166:169], v[146:161]
	s_add_u32 s4, s8, 0x120100
	s_addc_u32 s5, s9, 0
	s_add_i32 m0, s28, 0x6000
	s_nop 0
	global_load_lds_dwordx4 v226, s[4:5]
	v_mfma_f32_32x32x16_bf16 v[146:161], v[142:145], v[162:165], v[146:161]
	s_setprio 0
	ds_read_b128 v[130:133], v1 offset:8192
	ds_read_b128 v[194:197], v198 offset:8192
	ds_read_b128 v[198:201], v199 offset:8192
	ds_read_b128 v[202:205], v202 offset:8192
	s_setprio 1
	s_waitcnt lgkmcnt(0)
	v_mfma_f32_32x32x16_bf16 v[130:145], v[130:133], v[190:193], 0
	ds_read_b128 v[206:209], v206 offset:8192
	v_mfma_f32_32x32x16_bf16 v[130:145], v[194:197], v[186:189], v[130:145]
	ds_read_b128 v[194:197], v210 offset:8192
	v_mfma_f32_32x32x16_bf16 v[130:145], v[198:201], v[182:185], v[130:145]
	ds_read_b128 v[198:201], v212 offset:8192
	v_mfma_f32_32x32x16_bf16 v[130:145], v[202:205], v[178:181], v[130:145]
	ds_read_b128 v[202:205], v213 offset:8192
	s_waitcnt lgkmcnt(0)
	v_mfma_f32_32x32x16_bf16 v[130:145], v[206:209], v[174:177], v[130:145]
	v_mfma_f32_32x32x16_bf16 v[130:145], v[194:197], v[170:173], v[130:145]
	v_mfma_f32_32x32x16_bf16 v[130:145], v[198:201], v[166:169], v[130:145]
	v_mfma_f32_32x32x16_bf16 v[130:145], v[202:205], v[162:165], v[130:145]
	s_setprio 0
	v_add_u32_e32 v1, s29, v250
	ds_read_b64_tr_b16 v[206:207], v1 offset:32768
	ds_read_b64_tr_b16 v[208:209], v1 offset:36864
	ds_read_b64_tr_b16 v[200:201], v1 offset:37376
	ds_read_b64_tr_b16 v[198:199], v1 offset:33280
	ds_read_b64_tr_b16 v[202:203], v1 offset:40960
	ds_read_b64_tr_b16 v[204:205], v1 offset:45056
	ds_read_b64_tr_b16 v[196:197], v1 offset:45568
	ds_read_b64_tr_b16 v[194:195], v1 offset:41472
	s_cmpk_lt_i32 s26, 0xff62
	s_cselect_b32 s29, s19, s22
	s_add_i32 s4, s26, 0x9e
	s_cmp_lt_u32 s4, 0x13d
	s_cbranch_scc1 .Lattn_near0

; #define SBAR() __builtin_amdgcn_sched_barrier(0)
; template <int D0, int S> __device__ __forceinline__ VG vload(ldsc_t vb) { VG g; g.l0 = vtr(vb + v_rd_off(D0, 2 * S, 0)); g.h0 = vtr(vb + v_rd_off(D0, 2 * S, 1)); g.l1 = vtr(vb + v_rd_off(D0, 2 * S + 1, 0)); g.h1 = vtr(vb + v_rd_off(D0, 2 * S + 1, 1)); return g; }
; __device__ __forceinline__ void softmax_sub(f32x16& p, float& m_reg, float& l_reg, bf16x8& pa0, bf16x8& pa1, f32x16 (&o)[8], float* al_l, int r32, int hi, int dj, const float* tab, float cL, float cR) {
;     ...
;   const float mnC = (cb - mn) * C;
;   float ps = 0;
; #pragma unroll
;   for (int r = 0; r < 16; ++r) { p[r] = __builtin_amdgcn_exp2f(fmaf(p[r], C, mnC)); ps += p[r]; }
;   { auto rr = __builtin_amdgcn_permlane32_swap(__float_as_uint(ps), __float_as_uint(ps), false, false);
;     ps = __uint_as_float(rr[0]) + __uint_as_float(rr[1]); }
;   l_reg = l_reg * alpha + ps;
;     ...
;   PK4(p, 0, pa0); PK4(p, 8, pa1);
;     ...
; }
; template <int S, class Dma> __device__ __forceinline__ void pv_run(f32x16 (&o)[8], ldsc_t vb, VG g0, VG g1, bf16x8 pa0, bf16x8 pa1, const Dma& dma) {
;   SBAR(); __builtin_amdgcn_s_setprio(1);
;   vmma(o[0], g0, pa0, pa1); dma(0); SBAR(); g0 = vload<2, S>(vb); SBAR();
;   vmma(o[1], g1, pa0, pa1); dma(1); SBAR(); g1 = vload<3, S>(vb); SBAR();
;   vmma(o[2], g0, pa0, pa1); dma(2); SBAR(); g0 = vload<4, S>(vb); SBAR();
;   vmma(o[3], g1, pa0, pa1); dma(3); SBAR(); g1 = vload<5, S>(vb); SBAR();
;   vmma(o[4], g0, pa0, pa1); dma(4); SBAR(); g0 = vload<6, S>(vb); SBAR();
;   vmma(o[5], g1, pa0, pa1); dma(5); SBAR(); g1 = vload<7, S>(vb); SBAR();
;   vmma(o[6], g0, pa0, pa1); dma(6); SBAR(); vmma(o[7], g1, pa0, pa1); dma(7); __builtin_amdgcn_s_setprio(0); SBAR();
; __device__ __forceinline__ void attn_unit(const bf16* __restrict__ qkvb, int seq, int q0, int h, ldsp_t ldsb, float* wsc, const float* tab, float lam) {
;     ...
;       { VG g0 = vload<0, 1>(vp + bo), g1 = vload<1, 1>(vp + bo);
;         softmax_sub(p1, m_reg, l_reg, pa0, pa1, o, al_l, r32, hi, 64 * j + 32 - q0w, tab, cL, cR);
.LBB0_555:
	v_sub_f32_e32 v211, s29, v210
	v_mul_f32_e32 v211, 0x3e0293ee, v211
	v_fmamk_f32 v146, v146, 0x3e0293ee, v211
	v_exp_f32_e32 v146, v146
	v_fmamk_f32 v147, v147, 0x3e0293ee, v211
	v_exp_f32_e32 v147, v147
	v_fmamk_f32 v148, v148, 0x3e0293ee, v211
	v_exp_f32_e32 v148, v148
	v_fmamk_f32 v149, v149, 0x3e0293ee, v211
	v_exp_f32_e32 v149, v149
	v_fmamk_f32 v150, v150, 0x3e0293ee, v211
	v_add_f32_e32 v212, 0, v146
	v_exp_f32_e32 v150, v150
	v_fmamk_f32 v151, v151, 0x3e0293ee, v211
	v_add_f32_e32 v212, v147, v212
	v_exp_f32_e32 v151, v151
	v_fmamk_f32 v152, v152, 0x3e0293ee, v211
	v_add_f32_e32 v212, v148, v212
	v_exp_f32_e32 v152, v152
	v_fmamk_f32 v153, v153, 0x3e0293ee, v211
	v_add_f32_e32 v212, v149, v212
	v_exp_f32_e32 v153, v153
	v_fmamk_f32 v154, v154, 0x3e0293ee, v211
	v_add_f32_e32 v212, v150, v212
	v_exp_f32_e32 v154, v154
	v_fmamk_f32 v155, v155, 0x3e0293ee, v211
	v_add_f32_e32 v212, v151, v212
	v_exp_f32_e32 v155, v155
	v_fmamk_f32 v156, v156, 0x3e0293ee, v211
	v_add_f32_e32 v212, v152, v212
	v_exp_f32_e32 v156, v156
	v_fmamk_f32 v157, v157, 0x3e0293ee, v211
	v_add_f32_e32 v212, v153, v212
	v_exp_f32_e32 v157, v157
	v_fmamk_f32 v158, v158, 0x3e0293ee, v211
	v_add_f32_e32 v212, v154, v212
	v_exp_f32_e32 v158, v158
	v_fmamk_f32 v159, v159, 0x3e0293ee, v211
	v_add_f32_e32 v212, v155, v212
	v_exp_f32_e32 v159, v159
	v_fmamk_f32 v160, v160, 0x3e0293ee, v211
	v_add_f32_e32 v212, v156, v212
	v_exp_f32_e32 v160, v160
	v_fmac_f32_e32 v211, 0x3e0293ee, v161
	v_add_f32_e32 v212, v157, v212
	v_exp_f32_e32 v161, v211
	v_add_f32_e32 v211, v158, v212
	v_add_f32_e32 v211, v159, v211
	v_add_f32_e32 v211, v160, v211
	v_add_f32_e32 v212, v161, v211
	v_mov_b32_e32 v213, v212
	v_cvt_pk_bf16_f32 v146, v146, v147
	v_cvt_pk_bf16_f32 v147, v148, v149
	v_cvt_pk_bf16_f32 v148, v150, v151
	v_cvt_pk_bf16_f32 v149, v152, v153
	v_cvt_pk_bf16_f32 v150, v154, v155
	v_cvt_pk_bf16_f32 v151, v156, v157
	v_cvt_pk_bf16_f32 v152, v158, v159
	v_cvt_pk_bf16_f32 v153, v160, v161
	s_nop 1
	v_permlane32_swap_b32_e32 v212, v213
	v_permlane32_swap_b32_e32 v146, v148
	v_permlane32_swap_b32_e32 v147, v149
	v_permlane32_swap_b32_e32 v150, v152
	v_permlane32_swap_b32_e32 v151, v153
	s_setprio 1
	s_waitcnt lgkmcnt(0)
	v_mfma_f32_32x32x16_bf16 v[98:113], v[146:149], v[206:209], v[98:113]
	s_add_u32 s4, s8, 0xc0000
	s_addc_u32 s5, s9, 0
	s_add_i32 m0, s28, 0x8000
	s_nop 0
	global_load_lds_dwordx4 v238, s[4:5]
	v_mfma_f32_32x32x16_bf16 v[98:113], v[150:153], v[202:205], v[98:113]
	ds_read_b64_tr_b16 v[154:155], v1 offset:33792
	ds_read_b64_tr_b16 v[156:157], v1 offset:37888
	ds_read_b64_tr_b16 v[158:159], v1 offset:41984
	ds_read_b64_tr_b16 v[160:161], v1 offset:46080
	v_mfma_f32_32x32x16_bf16 v[114:129], v[146:149], v[198:201], v[114:129]
	s_add_u32 s4, s8, 0xf0000
	s_addc_u32 s5, s9, 0
	s_add_i32 m0, s28, 0xa000
	s_nop 0
	global_load_lds_dwordx4 v238, s[4:5]
	v_mfma_f32_32x32x16_bf16 v[114:129], v[150:153], v[194:197], v[114:129]
	ds_read_b64_tr_b16 v[194:195], v1 offset:34304
	ds_read_b64_tr_b16 v[196:197], v1 offset:38400
	ds_read_b64_tr_b16 v[198:199], v1 offset:42496
	ds_read_b64_tr_b16 v[200:201], v1 offset:46592
	s_waitcnt lgkmcnt(0)
	v_mfma_f32_32x32x16_bf16 v[66:81], v[146:149], v[154:157], v[66:81]
	s_add_u32 s4, s8, 0x120000
	s_addc_u32 s5, s9, 0
	s_add_i32 m0, s28, 0xc000
	s_nop 0
	global_load_lds_dwordx4 v238, s[4:5]
	v_mfma_f32_32x32x16_bf16 v[66:81], v[150:153], v[158:161], v[66:81]
	ds_read_b64_tr_b16 v[154:155], v1 offset:34816
	ds_read_b64_tr_b16 v[156:157], v1 offset:38912
	ds_read_b64_tr_b16 v[158:159], v1 offset:43008
	ds_read_b64_tr_b16 v[160:161], v1 offset:47104
	v_mfma_f32_32x32x16_bf16 v[82:97], v[146:149], v[194:197], v[82:97]
	s_add_u32 s4, s8, 0x150000
	s_addc_u32 s5, s9, 0
	s_add_i32 m0, s28, 0xe000
	s_nop 0
	global_load_lds_dwordx4 v238, s[4:5]
	v_mfma_f32_32x32x16_bf16 v[82:97], v[150:153], v[198:201], v[82:97]
	ds_read_b64_tr_b16 v[194:195], v1 offset:35328
	ds_read_b64_tr_b16 v[196:197], v1 offset:39424
	ds_read_b64_tr_b16 v[198:199], v1 offset:43520
	ds_read_b64_tr_b16 v[200:201], v1 offset:47616
	s_waitcnt lgkmcnt(0)
	v_mfma_f32_32x32x16_bf16 v[34:49], v[146:149], v[154:157], v[34:49]
	v_mfma_f32_32x32x16_bf16 v[34:49], v[150:153], v[158:161], v[34:49]
	ds_read_b64_tr_b16 v[154:155], v1 offset:35840
	ds_read_b64_tr_b16 v[156:157], v1 offset:39936
	ds_read_b64_tr_b16 v[158:159], v1 offset:44032
	ds_read_b64_tr_b16 v[160:161], v1 offset:48128
	v_mfma_f32_32x32x16_bf16 v[50:65], v[146:149], v[194:197], v[50:65]
	v_mfma_f32_32x32x16_bf16 v[50:65], v[150:153], v[198:201], v[50:65]
	ds_read_b64_tr_b16 v[194:195], v1 offset:36352
	ds_read_b64_tr_b16 v[196:197], v1 offset:40448
	ds_read_b64_tr_b16 v[198:199], v1 offset:44544
	ds_read_b64_tr_b16 v[200:201], v1 offset:48640
	s_waitcnt lgkmcnt(0)
	v_mfma_f32_32x32x16_bf16 v[18:33], v[146:149], v[154:157], v[18:33]
	v_mfma_f32_32x32x16_bf16 v[18:33], v[150:153], v[158:161], v[18:33]
	v_mfma_f32_32x32x16_bf16 v[2:17], v[146:149], v[194:197], v[2:17]
	v_mfma_f32_32x32x16_bf16 v[2:17], v[150:153], v[198:201], v[2:17]
	s_setprio 0
	ds_read_b64_tr_b16 v[154:155], v1 offset:49152
	ds_read_b64_tr_b16 v[156:157], v1 offset:53248
	ds_read_b64_tr_b16 v[152:153], v1 offset:53760
	ds_read_b64_tr_b16 v[150:151], v1 offset:49664
	ds_read_b64_tr_b16 v[158:159], v1 offset:57344
	ds_read_b64_tr_b16 v[160:161], v1 offset:61440
	ds_read_b64_tr_b16 v[148:149], v1 offset:61952
	ds_read_b64_tr_b16 v[146:147], v1 offset:57856
	s_add_i32 s4, s26, 32
	s_cmpk_lt_i32 s4, 0xff62
	s_cselect_b32 s28, s19, s22
	s_add_i32 s5, s4, 0x9e
	s_cmp_lt_u32 s5, 0x13d
	s_cbranch_scc1 .Lattn_near1

; __device__ __forceinline__ void softmax_sub(f32x16& p, float& m_reg, float& l_reg, bf16x8& pa0, bf16x8& pa1, f32x16 (&o)[8], float* al_l, int r32, int hi, int dj, const float* tab, float cL, float cR) {
;     ...
;   else { cb = 0.f; const int ib = dj - r32 + 4 * hi + 128;
; #pragma unroll
;     for (int r = 0; r < 16; ++r) { const int i0 = ib + (r & 3) + 8 * (r >> 2); p[r] += tab[min(max(i0, 0), 256)]; } }
.Lattn_near0:
	v_add_u32_e32 v210, s26, v245
	v_add_u32_e32 v210, 0x80, v210
	v_mov_b32_e32 v212, 0x100
	v_med3_i32 v212, v210, 0, v212
	v_lshl_add_u32 v220, v212, 2, s20
	v_max_i32_e32 v212, -1, v210
	v_add_u32_e32 v212, 1, v212
	v_min_u32_e32 v212, 0x100, v212
	v_lshl_add_u32 v221, v212, 2, s20
	v_max_i32_e32 v212, -2, v210
	v_add_u32_e32 v212, 2, v212
	v_min_u32_e32 v212, 0x100, v212
	v_lshl_add_u32 v222, v212, 2, s20
	v_max_i32_e32 v212, -3, v210
	v_add_u32_e32 v212, 3, v212
	v_min_u32_e32 v212, 0x100, v212
	v_lshl_add_u32 v223, v212, 2, s20
	v_max_i32_e32 v212, -8, v210
	v_add_u32_e32 v212, 8, v212
	v_min_u32_e32 v212, 0x100, v212
	v_lshl_add_u32 v224, v212, 2, s20
	v_max_i32_e32 v212, -9, v210
	v_add_u32_e32 v212, 9, v212
	v_min_u32_e32 v212, 0x100, v212
	v_lshl_add_u32 v225, v212, 2, s20
	v_max_i32_e32 v212, -10, v210
	v_add_u32_e32 v212, 10, v212
	v_min_u32_e32 v212, 0x100, v212
	v_lshl_add_u32 v232, v212, 2, s20
	v_max_i32_e32 v212, -11, v210
	v_add_u32_e32 v212, 11, v212
	v_min_u32_e32 v212, 0x100, v212
	v_lshl_add_u32 v233, v212, 2, s20
	v_max_i32_e32 v212, -16, v210
	v_max_i32_e32 v213, 0xffffffef, v210
	v_max_i32_e32 v214, 0xffffffee, v210
	v_max_i32_e32 v215, 0xffffffed, v210
	v_max_i32_e32 v216, 0xffffffe8, v210
	v_max_i32_e32 v217, 0xffffffe7, v210
	v_max_i32_e32 v218, 0xffffffe6, v210
	v_add_u32_e32 v212, 16, v212
	v_add_u32_e32 v213, 17, v213
	v_add_u32_e32 v214, 18, v214
	v_add_u32_e32 v215, 19, v215
	v_add_u32_e32 v216, 24, v216
	v_add_u32_e32 v217, 25, v217
	v_add_u32_e32 v218, 26, v218
	v_max_i32_e32 v210, 0xffffffe5, v210
	v_min_u32_e32 v212, 0x100, v212
	v_min_u32_e32 v213, 0x100, v213
	v_min_u32_e32 v214, 0x100, v214
	v_min_u32_e32 v215, 0x100, v215
	v_min_u32_e32 v216, 0x100, v216
	v_min_u32_e32 v217, 0x100, v217
	v_min_u32_e32 v218, 0x100, v218
	v_add_u32_e32 v210, 27, v210
	v_lshl_add_u32 v212, v212, 2, s20
	v_lshl_add_u32 v213, v213, 2, s20
	v_lshl_add_u32 v214, v214, 2, s20
	v_lshl_add_u32 v215, v215, 2, s20
	v_lshl_add_u32 v216, v216, 2, s20
	v_lshl_add_u32 v217, v217, 2, s20
	v_lshl_add_u32 v218, v218, 2, s20
	v_min_u32_e32 v210, 0x100, v210
	v_lshl_add_u32 v210, v210, 2, s20
	ds_read_b32 v212, v212
	ds_read_b32 v213, v213
	ds_read_b32 v214, v214
	ds_read_b32 v215, v215
	ds_read_b32 v216, v216
	ds_read_b32 v217, v217
	ds_read_b32 v218, v218
	ds_read_b32 v219, v210
	ds_read_b32 v220, v220
	ds_read_b32 v221, v221
	ds_read_b32 v222, v222
	ds_read_b32 v223, v223
	ds_read_b32 v224, v224
	ds_read_b32 v225, v225
	ds_read_b32 v232, v232
	ds_read_b32 v233, v233
	s_waitcnt lgkmcnt(0)
	v_pk_add_f32 v[160:161], v[160:161], v[218:219]
	v_pk_add_f32 v[158:159], v[158:159], v[216:217]
	v_pk_add_f32 v[156:157], v[156:157], v[214:215]
	v_pk_add_f32 v[154:155], v[154:155], v[212:213]
	v_pk_add_f32 v[152:153], v[152:153], v[232:233]
	v_pk_add_f32 v[150:151], v[150:151], v[224:225]
	v_pk_add_f32 v[148:149], v[148:149], v[222:223]
	v_pk_add_f32 v[146:147], v[146:147], v[220:221]
	s_mov_b32 s29, 0
	s_branch .LBB0_553
.Lattn_near1:
	v_add_u32_e32 v194, s26, v245
	v_add_u32_e32 v194, 0xa0, v194
	v_mov_b32_e32 v195, 0x100
	v_med3_i32 v195, v194, 0, v195
	v_lshl_add_u32 v202, v195, 2, s20
	v_max_i32_e32 v195, -1, v194
	v_add_u32_e32 v195, 1, v195
	v_min_u32_e32 v195, 0x100, v195
	v_lshl_add_u32 v203, v195, 2, s20
	v_max_i32_e32 v195, -2, v194
	v_add_u32_e32 v195, 2, v195
	v_min_u32_e32 v195, 0x100, v195
	v_lshl_add_u32 v204, v195, 2, s20
	v_max_i32_e32 v195, -3, v194
	v_add_u32_e32 v195, 3, v195
	v_min_u32_e32 v195, 0x100, v195
	v_lshl_add_u32 v205, v195, 2, s20
	v_max_i32_e32 v195, -8, v194
	v_add_u32_e32 v195, 8, v195
	v_min_u32_e32 v195, 0x100, v195
	v_lshl_add_u32 v206, v195, 2, s20
	v_max_i32_e32 v195, -9, v194
	v_add_u32_e32 v195, 9, v195
	v_min_u32_e32 v195, 0x100, v195
	v_lshl_add_u32 v207, v195, 2, s20
	v_max_i32_e32 v195, -10, v194
	v_add_u32_e32 v195, 10, v195
	v_min_u32_e32 v195, 0x100, v195
	v_lshl_add_u32 v208, v195, 2, s20
	v_max_i32_e32 v195, -11, v194
	v_add_u32_e32 v195, 11, v195
	v_min_u32_e32 v195, 0x100, v195
	v_lshl_add_u32 v209, v195, 2, s20
	v_max_i32_e32 v195, -16, v194
	v_max_i32_e32 v196, 0xffffffef, v194
	v_max_i32_e32 v197, 0xffffffee, v194
	v_max_i32_e32 v198, 0xffffffed, v194
	v_max_i32_e32 v199, 0xffffffe8, v194
	v_max_i32_e32 v200, 0xffffffe7, v194
	v_max_i32_e32 v201, 0xffffffe6, v194
	v_add_u32_e32 v195, 16, v195
	v_add_u32_e32 v196, 17, v196
	v_add_u32_e32 v197, 18, v197
	v_add_u32_e32 v198, 19, v198
	v_add_u32_e32 v199, 24, v199
	v_add_u32_e32 v200, 25, v200
	v_add_u32_e32 v201, 26, v201
	v_max_i32_e32 v194, 0xffffffe5, v194
	v_min_u32_e32 v195, 0x100, v195
	v_min_u32_e32 v196, 0x100, v196
	v_min_u32_e32 v197, 0x100, v197
	v_min_u32_e32 v198, 0x100, v198
	v_min_u32_e32 v199, 0x100, v199
	v_min_u32_e32 v200, 0x100, v200
	v_min_u32_e32 v201, 0x100, v201
	v_add_u32_e32 v194, 27, v194
	v_lshl_add_u32 v195, v195, 2, s20
	v_lshl_add_u32 v196, v196, 2, s20
	v_lshl_add_u32 v197, v197, 2, s20
	v_lshl_add_u32 v198, v198, 2, s20
	v_lshl_add_u32 v199, v199, 2, s20
	v_lshl_add_u32 v200, v200, 2, s20
	v_lshl_add_u32 v201, v201, 2, s20
	v_min_u32_e32 v194, 0x100, v194
	v_lshl_add_u32 v211, v194, 2, s20
	ds_read_b32 v194, v195
	ds_read_b32 v195, v196
	ds_read_b32 v196, v197
	ds_read_b32 v197, v198
	ds_read_b32 v198, v199
	ds_read_b32 v199, v200
	ds_read_b32 v200, v201
	ds_read_b32 v201, v211
	ds_read_b32 v202, v202
	ds_read_b32 v203, v203
	ds_read_b32 v204, v204
	ds_read_b32 v205, v205
	ds_read_b32 v206, v206
	ds_read_b32 v207, v207
	ds_read_b32 v208, v208
	ds_read_b32 v209, v209
	s_waitcnt lgkmcnt(0)
	v_pk_add_f32 v[144:145], v[144:145], v[200:201]
	v_pk_add_f32 v[142:143], v[142:143], v[198:199]
	v_pk_add_f32 v[140:141], v[140:141], v[196:197]
	v_pk_add_f32 v[138:139], v[138:139], v[194:195]
	v_pk_add_f32 v[136:137], v[136:137], v[208:209]
	v_pk_add_f32 v[134:135], v[134:135], v[206:207]
	v_pk_add_f32 v[132:133], v[132:133], v[204:205]
	v_pk_add_f32 v[130:131], v[130:131], v[202:203]
	s_mov_b32 s28, 0
	s_branch .LBB0_560
